# RG-LRU: rows-hi gate gather issued before the rows-hi K-fragment loads, latch wait relaxed to vmcnt(9) so it no longer waits on those fragments
# speedup vs baseline: 1.0016x; 1.0016x over previous
; __device__ __forceinline__ unsigned cvt_pk_bf16(float lo, float hi) { unsigned r; asm volatile("v_cvt_pk_bf16_f32 %0, %1, %2" : "=v"(r) : "v"(lo), "v"(hi)); return r; }
; __device__ __forceinline__ float bf_lo(unsigned w) { return __uint_as_float(w << 16); }
; __device__ __forceinline__ float bf_hi(unsigned w) { return __uint_as_float(w & 0xffff0000u); }
; __device__ __forceinline__ float fast_rcp(float x) { return __builtin_amdgcn_rcpf(x); }
; __device__ __forceinline__ void lru_fused(const bf16* XC, const bf16* Wrg_t, const bf16* PROJ, bf16* YL, const float* b_a, const float* b_x, const float* sp8,
;                                           LAS unsigned char* lds, int tid, int lane, int wave, int vcu, int G) {
;     ...
;             for (int r2 = 0; r2 < 2; ++r2) { const size_t ro = (row0 + 16 * r2 + fr) * D;
; #pragma unroll
;                 for (int c2 = 0; c2 < 2; ++c2) { const v2u gw = gq[r2][c2]; const float gg[4] = {bf_lo(gw.x), bf_hi(gw.x), bf_lo(gw.y), bf_hi(gw.y)}; float y[4];
; #pragma unroll
;                     for (int j = 0; j < 4; ++j) { const float hh = U[r2][c2][j] + A[r2][c2][j] * hin[c2][j]; const float gx = gg[j], gz = gx * __builtin_fmaf(gx * gx, -0.10294324f, -2.30220819f);
;                         y[j] = hh * gx * pg8::fast_rcp(1.0f + __builtin_amdgcn_exp2f(gz)); }
;                     v2u o; o.x = cvt_pk_bf16(y[0], y[1]); o.y = cvt_pk_bf16(y[2], y[3]); *(v2u*)(obase + ro + 16 * c2) = o; } }
; #pragma unroll
;             for (int r2 = 0; r2 < 2; ++r2)
; #pragma unroll
;                 for (int c2 = 0; c2 < 2; ++c2) { xq[r2][c2] = xqn[r2][c2]; gq[r2][c2] = gqn[r2][c2]; }
.LBB0_455:
	s_or_b64 exec, exec, s[66:67]
	v_lshlrev_b32_e32 v3, 16, v158
	s_waitcnt lgkmcnt(0)
	v_fmac_f32_e32 v175, v173, v106
	v_mul_f32_e32 v173, v3, v3
	v_fmamk_f32 v173, v173, 0xbdd2d3e8, v171
	v_mul_f32_e32 v173, v173, v3
	v_exp_f32_e32 v173, v173
	v_and_b32_e32 v158, 0xffff0000, v158
	v_lshlrev_b32_e32 v192, 16, v159
	v_and_b32_e32 v159, 0xffff0000, v159
	v_add_f32_e32 v173, 1.0, v173
	v_rcp_f32_e32 v173, v173
	v_mul_f32_e32 v193, v158, v158
	v_mul_f32_e32 v3, v175, v3
	v_fmac_f32_e32 v177, v174, v107
	v_mul_f32_e32 v174, v159, v159
	v_fmamk_f32 v193, v193, 0xbdd2d3e8, v171
	v_mul_f32_e32 v3, v173, v3
	v_mul_f32_e32 v173, v192, v192
	v_fmamk_f32 v174, v174, 0xbdd2d3e8, v171
	v_mul_f32_e32 v193, v193, v158
	v_fmamk_f32 v173, v173, 0xbdd2d3e8, v171
	v_mul_f32_e32 v174, v174, v159
	v_exp_f32_e32 v193, v193
	v_mul_f32_e32 v173, v173, v192
	v_exp_f32_e32 v174, v174
	v_exp_f32_e32 v173, v173
	v_add_f32_e32 v175, 1.0, v193
	v_rcp_f32_e32 v175, v175
	v_add_f32_e32 v174, 1.0, v174
	v_add_f32_e32 v173, 1.0, v173
	v_rcp_f32_e32 v174, v174
	v_rcp_f32_e32 v173, v173
	v_fmac_f32_e32 v182, v176, v109
	v_lshl_add_u64 v[4:5], v[130:131], 0, s[64:65]
	v_mul_f32_e32 v158, v177, v158
	v_fmac_f32_e32 v184, v181, v108
	v_mul_f32_e32 v159, v182, v159
	v_mul_f32_e32 v158, v175, v158
	v_mul_f32_e32 v175, v184, v192
	v_mul_f32_e32 v159, v174, v159
	v_add_co_u32_e32 v4, vcc, s17, v4
	v_mul_f32_e32 v173, v173, v175
	v_cvt_pk_bf16_f32 v252, v3, v158
	v_cvt_pk_bf16_f32 v253, v173, v159
	s_nop 0
	v_addc_co_u32_e32 v5, vcc, 0, v5, vcc
	v_lshlrev_b32_e32 v3, 16, v152
	v_and_b32_e32 v152, 0xffff0000, v152
	v_mul_f32_e32 v159, v3, v3
	v_mul_f32_e32 v173, v152, v152
	v_fmamk_f32 v159, v159, 0xbdd2d3e8, v171
	v_fmamk_f32 v173, v173, 0xbdd2d3e8, v171
	v_mul_f32_e32 v159, v159, v3
	v_mul_f32_e32 v173, v173, v152
	v_exp_f32_e32 v159, v159
	v_exp_f32_e32 v173, v173
	v_fmac_f32_e32 v186, v183, v102
	v_fmac_f32_e32 v188, v185, v103
	v_add_f32_e32 v159, 1.0, v159
	v_add_f32_e32 v173, 1.0, v173
	v_rcp_f32_e32 v159, v159
	v_rcp_f32_e32 v173, v173
	v_lshlrev_b32_e32 v158, 16, v153
	v_and_b32_e32 v153, 0xffff0000, v153
	v_mul_f32_e32 v3, v186, v3
	v_mul_f32_e32 v152, v188, v152
	v_mul_f32_e32 v3, v159, v3
	v_mul_f32_e32 v152, v173, v152
	v_mul_f32_e32 v173, v153, v153
	v_mul_f32_e32 v159, v158, v158
	v_fmamk_f32 v173, v173, 0xbdd2d3e8, v171
	v_cvt_pk_bf16_f32 v254, v3, v152
	v_lshlrev_b32_e32 v3, 16, v146
	v_and_b32_e32 v146, 0xffff0000, v146
	v_fmamk_f32 v159, v159, 0xbdd2d3e8, v171
	v_mul_f32_e32 v173, v173, v153
	v_fma_f32 v94, v98, v106, v94
	v_mul_f32_e32 v106, v146, v146
	v_mul_f32_e32 v159, v159, v158
	v_exp_f32_e32 v173, v173
	v_mul_f32_e32 v98, v3, v3
	v_fmamk_f32 v106, v106, 0xbdd2d3e8, v171
	v_exp_f32_e32 v159, v159
	v_fmamk_f32 v98, v98, 0xbdd2d3e8, v171
	v_mul_f32_e32 v106, v106, v146
	v_mul_f32_e32 v98, v98, v3
	v_exp_f32_e32 v106, v106
	v_exp_f32_e32 v98, v98
	v_add_f32_e32 v173, 1.0, v173
	v_add_f32_e32 v159, 1.0, v159
	v_rcp_f32_e32 v173, v173
	v_rcp_f32_e32 v159, v159
	v_mul_f32_e32 v3, v94, v3
	v_add_f32_e32 v94, 1.0, v106
	v_fmac_f32_e32 v190, v187, v105
	v_add_f32_e32 v98, 1.0, v98
	v_rcp_f32_e32 v94, v94
	v_fmac_f32_e32 v191, v189, v104
	v_mul_f32_e32 v153, v190, v153
	v_rcp_f32_e32 v98, v98
	v_mul_f32_e32 v158, v191, v158
	v_mul_f32_e32 v153, v173, v153
	v_fmac_f32_e32 v95, v99, v107
	v_mul_f32_e32 v158, v159, v158
	v_cvt_pk_bf16_f32 v255, v158, v153
	global_store_dwordx4 v[4:5], v[252:255], off
	v_lshlrev_b32_e32 v152, 16, v147
	v_mul_f32_e32 v95, v95, v146
	v_and_b32_e32 v147, 0xffff0000, v147
	v_mul_f32_e32 v94, v94, v95
	v_fma_f32 v95, v100, v108, v96
	v_mul_f32_e32 v96, v152, v152
	v_mul_f32_e32 v3, v98, v3
	v_fmamk_f32 v96, v96, 0xbdd2d3e8, v171
	v_mul_f32_e32 v98, v147, v147
	v_mul_f32_e32 v96, v96, v152
	v_fmamk_f32 v98, v98, 0xbdd2d3e8, v171
	v_exp_f32_e32 v96, v96
	v_mul_f32_e32 v98, v98, v147
	v_exp_f32_e32 v98, v98
	v_lshl_add_u64 v[4:5], v[128:129], 0, s[64:65]
	v_add_f32_e32 v96, 1.0, v96
	v_rcp_f32_e32 v96, v96
	v_add_f32_e32 v98, 1.0, v98
	v_rcp_f32_e32 v98, v98
	v_mul_f32_e32 v95, v95, v152
	v_fmac_f32_e32 v97, v101, v109
	v_add_co_u32_e32 v4, vcc, s17, v4
	v_mul_f32_e32 v95, v96, v95
	v_mul_f32_e32 v96, v97, v147
	v_cvt_pk_bf16_f32 v252, v3, v94
	v_addc_co_u32_e32 v5, vcc, 0, v5, vcc
	v_mul_f32_e32 v96, v98, v96
	v_cvt_pk_bf16_f32 v253, v95, v96
	s_waitcnt vmcnt(27)
	v_and_b32_e32 v94, 0xffff0000, v140
	v_lshlrev_b32_e32 v3, 16, v140
	v_mul_f32_e32 v97, v94, v94
	v_fma_f32 v86, v90, v102, v86
	v_mul_f32_e32 v90, v3, v3
	v_fmamk_f32 v97, v97, 0xbdd2d3e8, v171
	v_fmamk_f32 v90, v90, 0xbdd2d3e8, v171
	v_mul_f32_e32 v97, v97, v94
	v_mul_f32_e32 v90, v90, v3
	v_exp_f32_e32 v97, v97
	v_exp_f32_e32 v90, v90
	v_mul_f32_e32 v3, v86, v3
	v_fmac_f32_e32 v87, v91, v103
	v_add_f32_e32 v86, 1.0, v97
	v_add_f32_e32 v90, 1.0, v90
	v_rcp_f32_e32 v86, v86
	v_rcp_f32_e32 v90, v90
	v_lshlrev_b32_e32 v95, 16, v141
	v_mul_f32_e32 v87, v87, v94
	v_and_b32_e32 v96, 0xffff0000, v141
	v_mul_f32_e32 v86, v86, v87
	v_fma_f32 v87, v92, v104, v88
	v_mul_f32_e32 v88, v95, v95
	v_mul_f32_e32 v3, v90, v3
	v_fmamk_f32 v88, v88, 0xbdd2d3e8, v171
	v_mul_f32_e32 v90, v96, v96
	v_mul_f32_e32 v88, v88, v95
	v_fmamk_f32 v90, v90, 0xbdd2d3e8, v171
	v_exp_f32_e32 v88, v88
	v_mul_f32_e32 v90, v90, v96
	v_exp_f32_e32 v90, v90
	s_add_u32 s64, s64, 0x200000
	v_add_f32_e32 v88, 1.0, v88
	v_rcp_f32_e32 v88, v88
	v_add_f32_e32 v90, 1.0, v90
	v_rcp_f32_e32 v90, v90
	s_addc_u32 s65, s65, 0
	s_add_u32 s19, s19, 0x100
	v_mul_f32_e32 v87, v87, v95
	v_fmac_f32_e32 v89, v93, v105
	s_addc_u32 s20, s20, 0
	s_add_i32 s21, s21, 32
	s_add_i32 s22, s22, 1
	v_mul_f32_e32 v87, v88, v87
	v_mul_f32_e32 v88, v89, v96
	s_cmp_eq_u32 s64, 0x4000000
	s_waitcnt vmcnt(9)
	v_mov_b64_e32 v[140:141], v[162:163]
	v_mov_b64_e32 v[146:147], v[160:161]
	v_mov_b64_e32 v[152:153], v[156:157]
	v_mov_b64_e32 v[158:159], v[154:155]
	v_mul_f32_e32 v88, v90, v88
	v_cvt_pk_bf16_f32 v254, v3, v86
	v_cvt_pk_bf16_f32 v255, v87, v88
	global_store_dwordx4 v[4:5], v[252:255], off
	s_cbranch_scc1 .LBB0_453

; #define LAS __attribute__((address_space(3)))
; __device__ __forceinline__ void lru_fused(const bf16* XC, const bf16* Wrg_t, const bf16* PROJ, bf16* YL, const float* b_a, const float* b_x, const float* sp8,
;                                           LAS unsigned char* lds, int tid, int lane, int wave, int vcu, int G) {
;     ...
;                 for (int kb = 0; kb < 8; ++kb) {
;                     if (kb + 1 < 8) {
; #pragma unroll
;                         for (int cb = 0; cb < 4; ++cb) bq[(kb + 1) & 1][cb] = *(const LAS bf16x8*)(bl + cb * 16 * RG_PITCH + (kb + 1) * 64); }
;                     __builtin_amdgcn_sched_barrier(0);
; #pragma unroll
;                     for (int cb = 0; cb < 4; ++cb)
; #pragma unroll
;                         for (int r2 = 0; r2 < 2; ++r2) acc[r2][cb] = __builtin_amdgcn_mfma_f32_16x16x32_bf16(bq[kb & 1][cb], af[r2][kb], acc[r2][cb], 0, 0, 0);
;                     __builtin_amdgcn_sched_barrier(0);
;                 }
.Lxq_done:
	s_waitcnt lgkmcnt(7)
	v_mfma_f32_16x16x32_bf16 v[142:145], v[86:89], v[70:73], 0
	v_mfma_f32_16x16x32_bf16 v[86:89], v[86:89], v[82:85], 0
	s_waitcnt lgkmcnt(5)
	v_mfma_f32_16x16x32_bf16 v[148:151], v[94:97], v[70:73], 0
	v_mfma_f32_16x16x32_bf16 v[94:97], v[94:97], v[82:85], 0
	s_waitcnt lgkmcnt(3)
	v_mfma_f32_16x16x32_bf16 v[182:185], v[106:109], v[70:73], 0
	v_mfma_f32_16x16x32_bf16 v[106:109], v[106:109], v[82:85], 0
	s_waitcnt lgkmcnt(1)
	v_mfma_f32_16x16x32_bf16 v[70:73], v[160:163], v[70:73], 0
	v_mfma_f32_16x16x32_bf16 v[82:85], v[160:163], v[82:85], 0
	ds_read_b128 v[160:163], v170 offset:128
	ds_read_b128 v[186:189], v170 offset:2304
	ds_read_b128 v[190:193], v170 offset:17536
	ds_read_b128 v[194:197], v170 offset:19712
	v_mfma_f32_16x16x32_bf16 v[142:145], v[90:93], v[62:65], v[142:145]
	v_mfma_f32_16x16x32_bf16 v[86:89], v[90:93], v[78:81], v[86:89]
	v_mfma_f32_16x16x32_bf16 v[90:93], v[98:101], v[62:65], v[148:151]
	v_mfma_f32_16x16x32_bf16 v[94:97], v[98:101], v[78:81], v[94:97]
	v_mfma_f32_16x16x32_bf16 v[98:101], v[154:157], v[62:65], v[182:185]
	s_waitcnt lgkmcnt(4)
	v_mfma_f32_16x16x32_bf16 v[62:65], v[174:177], v[62:65], v[70:73]
	v_mfma_f32_16x16x32_bf16 v[70:73], v[174:177], v[78:81], v[82:85]
	v_mfma_f32_16x16x32_bf16 v[106:109], v[154:157], v[78:81], v[106:109]
	ds_read_b128 v[78:81], v170 offset:192
	s_nop 0
	ds_read_b128 v[82:85], v170 offset:2368
	ds_read_b128 v[148:151], v170 offset:17600
	ds_read_b128 v[154:157], v170 offset:19776
	s_waitcnt lgkmcnt(7)
	v_mfma_f32_16x16x32_bf16 v[142:145], v[160:163], v[54:57], v[142:145]
	v_mfma_f32_16x16x32_bf16 v[86:89], v[160:163], v[74:77], v[86:89]
	s_waitcnt lgkmcnt(6)
	v_mfma_f32_16x16x32_bf16 v[90:93], v[186:189], v[54:57], v[90:93]
	v_mfma_f32_16x16x32_bf16 v[94:97], v[186:189], v[74:77], v[94:97]
	s_waitcnt lgkmcnt(5)
	v_mfma_f32_16x16x32_bf16 v[98:101], v[190:193], v[54:57], v[98:101]
	s_waitcnt lgkmcnt(4)
	v_mfma_f32_16x16x32_bf16 v[54:57], v[194:197], v[54:57], v[62:65]
	v_mfma_f32_16x16x32_bf16 v[62:65], v[194:197], v[74:77], v[70:73]
	v_mfma_f32_16x16x32_bf16 v[106:109], v[190:193], v[74:77], v[106:109]
	s_nop 1
	ds_read_b128 v[70:73], v170 offset:256
	ds_read_b128 v[74:77], v170 offset:2432
	ds_read_b128 v[160:163], v170 offset:17664
	ds_read_b128 v[174:177], v170 offset:19840
	s_waitcnt lgkmcnt(7)
	v_mfma_f32_16x16x32_bf16 v[142:145], v[78:81], v[46:49], v[142:145]
	v_mfma_f32_16x16x32_bf16 v[78:81], v[78:81], v[66:69], v[86:89]
	s_waitcnt lgkmcnt(6)
	v_mfma_f32_16x16x32_bf16 v[86:89], v[82:85], v[46:49], v[90:93]
	v_mfma_f32_16x16x32_bf16 v[82:85], v[82:85], v[66:69], v[94:97]
	s_waitcnt lgkmcnt(5)
	v_mfma_f32_16x16x32_bf16 v[90:93], v[148:151], v[46:49], v[98:101]
	v_mfma_f32_16x16x32_bf16 v[94:97], v[148:151], v[66:69], v[106:109]
	s_waitcnt lgkmcnt(4)
	v_mfma_f32_16x16x32_bf16 v[46:49], v[154:157], v[46:49], v[54:57]
	v_mfma_f32_16x16x32_bf16 v[54:57], v[154:157], v[66:69], v[62:65]
	s_nop 2
	ds_read_b128 v[62:65], v170 offset:320
	ds_read_b128 v[66:69], v170 offset:2496
	ds_read_b128 v[98:101], v170 offset:17728
	ds_read_b128 v[106:109], v170 offset:19904
	s_waitcnt lgkmcnt(7)
	v_mfma_f32_16x16x32_bf16 v[142:145], v[70:73], v[34:37], v[142:145]
	v_mfma_f32_16x16x32_bf16 v[70:73], v[70:73], v[58:61], v[78:81]
	s_waitcnt lgkmcnt(6)
	v_mfma_f32_16x16x32_bf16 v[78:81], v[74:77], v[34:37], v[86:89]
	v_mfma_f32_16x16x32_bf16 v[74:77], v[74:77], v[58:61], v[82:85]
	s_waitcnt lgkmcnt(5)
	v_mfma_f32_16x16x32_bf16 v[82:85], v[160:163], v[34:37], v[90:93]
	v_mfma_f32_16x16x32_bf16 v[86:89], v[160:163], v[58:61], v[94:97]
	s_waitcnt lgkmcnt(4)
	v_mfma_f32_16x16x32_bf16 v[34:37], v[174:177], v[34:37], v[46:49]
	v_mfma_f32_16x16x32_bf16 v[46:49], v[174:177], v[58:61], v[54:57]
	s_nop 2
	ds_read_b128 v[54:57], v170 offset:384
	ds_read_b128 v[58:61], v170 offset:2560
	ds_read_b128 v[90:93], v170 offset:17792
	ds_read_b128 v[94:97], v170 offset:19968
	s_waitcnt lgkmcnt(7)
	v_mfma_f32_16x16x32_bf16 v[142:145], v[62:65], v[30:33], v[142:145]
	v_mfma_f32_16x16x32_bf16 v[62:65], v[62:65], v[50:53], v[70:73]
	s_waitcnt lgkmcnt(6)
	v_mfma_f32_16x16x32_bf16 v[70:73], v[66:69], v[30:33], v[78:81]
	v_mfma_f32_16x16x32_bf16 v[66:69], v[66:69], v[50:53], v[74:77]
	s_waitcnt lgkmcnt(5)
	v_mfma_f32_16x16x32_bf16 v[74:77], v[98:101], v[30:33], v[82:85]
	v_mfma_f32_16x16x32_bf16 v[78:81], v[98:101], v[50:53], v[86:89]
	s_waitcnt lgkmcnt(4)
	v_mfma_f32_16x16x32_bf16 v[30:33], v[106:109], v[30:33], v[34:37]
	v_mfma_f32_16x16x32_bf16 v[34:37], v[106:109], v[50:53], v[46:49]
	s_nop 2
	ds_read_b128 v[46:49], v170 offset:448
	ds_read_b128 v[50:53], v170 offset:2624
	ds_read_b128 v[82:85], v170 offset:17856
	ds_read_b128 v[86:89], v170 offset:20032
	s_waitcnt lgkmcnt(7)
	v_mfma_f32_16x16x32_bf16 v[98:101], v[54:57], v[26:29], v[142:145]
	v_mfma_f32_16x16x32_bf16 v[54:57], v[54:57], v[42:45], v[62:65]
	s_waitcnt lgkmcnt(6)
	v_mfma_f32_16x16x32_bf16 v[62:65], v[58:61], v[26:29], v[70:73]
	v_mfma_f32_16x16x32_bf16 v[58:61], v[58:61], v[42:45], v[66:69]
	s_waitcnt lgkmcnt(5)
	v_mfma_f32_16x16x32_bf16 v[66:69], v[90:93], v[26:29], v[74:77]
	v_mfma_f32_16x16x32_bf16 v[70:73], v[90:93], v[42:45], v[78:81]
	s_waitcnt lgkmcnt(4)
	v_mfma_f32_16x16x32_bf16 v[26:29], v[94:97], v[26:29], v[30:33]
	v_mfma_f32_16x16x32_bf16 v[30:33], v[94:97], v[42:45], v[34:37]
	s_waitcnt lgkmcnt(3)
	v_mfma_f32_16x16x32_bf16 v[106:109], v[46:49], v[22:25], v[98:101]
	v_mfma_f32_16x16x32_bf16 v[98:101], v[46:49], v[38:41], v[54:57]
	s_waitcnt lgkmcnt(2)
	v_mfma_f32_16x16x32_bf16 v[188:191], v[50:53], v[22:25], v[62:65]
	v_mfma_f32_16x16x32_bf16 v[90:93], v[50:53], v[38:41], v[58:61]
	s_waitcnt lgkmcnt(1)
; __device__ __forceinline__ float bf_lo(unsigned w) { return __uint_as_float(w << 16); }
; __device__ __forceinline__ float bf_hi(unsigned w) { return __uint_as_float(w & 0xffff0000u); }
; __device__ __forceinline__ float sigmoidf_(float x) { return fast_rcp(1.0f + fast_exp(-x)); }
; __device__ __forceinline__ void lru_fused(const bf16* XC, const bf16* Wrg_t, const bf16* PROJ, bf16* YL, const float* b_a, const float* b_x, const float* sp8,
;                                           LAS unsigned char* lds, int tid, int lane, int wave, int vcu, int G) {
;     ...
;             { const size_t rown = (i + 1 < SEQ / 256) ? row0 + 256 : row0;
; #pragma unroll
;                 for (int r2 = 0; r2 < 2; ++r2) { const size_t ro = (rown + 16 * r2 + fr) * D, rg = (rown + 16 * r2 + fr) * NIN;
; #pragma unroll
;                     for (int kb = 0; kb < 8; ++kb) af[r2][kb] = *(const bf16x8*)(abase + ro + 32 * kb);
; #pragma unroll
;                     for (int c2 = 0; c2 < 2; ++c2) { xqn[r2][c2] = *(const v2u*)(xbase + ro + 16 * c2); gqn[r2][c2] = *(const v2u*)(gbase + rg + 16 * c2); } } }
;             float A[2][2][4], U[2][2][4];
; #pragma unroll
;             for (int r2 = 0; r2 < 2; ++r2)
; #pragma unroll
;                 for (int c2 = 0; c2 < 2; ++c2) { const f32x4 rp = acc[r2][c2] + ba[c2], ip = acc[r2][c2 + 2] + bx[c2]; const v2u xw = xq[r2][c2];
;                     const float xv[4] = {bf_lo(xw.x), bf_hi(xw.x), bf_lo(xw.y), bf_hi(xw.y)};
; #pragma unroll
;                     for (int j = 0; j < 4; ++j) { const float r = pg8::sigmoidf_(rp[j]), ig = pg8::sigmoidf_(ip[j]);
;                         const float av = __builtin_amdgcn_exp2f(sp[c2][j] * r);
;                         A[r2][c2][j] = av; U[r2][c2][j] = __builtin_amdgcn_sqrtf(fmaxf(__builtin_fmaf(-av, av, 1.0f), 0.0f)) * (ig * xv[j]); } }
	v_mfma_f32_16x16x32_bf16 v[182:185], v[82:85], v[22:25], v[66:69]
	v_mfma_f32_16x16x32_bf16 v[94:97], v[82:85], v[38:41], v[70:73]
	s_waitcnt lgkmcnt(0)
	v_mfma_f32_16x16x32_bf16 v[192:195], v[86:89], v[22:25], v[26:29]
	v_mfma_f32_16x16x32_bf16 v[86:89], v[86:89], v[38:41], v[30:33]
	v_add_f32_e32 v3, v6, v106
	v_mul_f32_e32 v3, 0xbfb8aa3b, v3
	v_exp_f32_e32 v3, v3
	s_add_u32 s23, s19, 0xffffff00
	s_addc_u32 s24, s20, -1
	s_cmp_eq_u32 s64, 0x3e00000
	s_cselect_b32 s25, s24, s20
	s_cselect_b32 s24, s23, s19
	v_mov_b32_e32 v39, s25
	v_or_b32_e32 v38, s24, v110
	v_lshlrev_b64 v[40:41], 13, v[38:39]
	v_mad_u64_u32 v[38:39], s[26:27], v38, s13, v[126:127]
	s_mul_i32 s23, s25, 0xa000
	v_lshl_add_u64 v[22:23], v[122:123], 0, v[40:41]
	v_lshl_add_u64 v[40:41], v[124:125], 0, v[40:41]
	v_add_u32_e32 v39, s23, v39
	global_load_dwordx4 v[70:73], v[22:23], off
	s_nop 0
	v_add_f32_e32 v173, v14, v182
	v_mul_f32_e32 v173, 0xbfb8aa3b, v173
	v_exp_f32_e32 v174, v173
	v_add_f32_e32 v3, 1.0, v3
	v_rcp_f32_e32 v3, v3
	v_add_f32_e32 v107, v7, v107
	v_add_f32_e32 v174, 1.0, v174
	v_mul_f32_e32 v107, 0xbfb8aa3b, v107
	v_mul_f32_e32 v3, v134, v3
	v_exp_f32_e32 v173, v3
	v_rcp_f32_e32 v174, v174
	v_exp_f32_e32 v107, v107
	v_lshlrev_b32_e32 v106, 16, v198
	v_fma_f32 v175, -v173, v173, 1.0
	global_load_dwordx4 v[62:65], v[22:23], off offset:64
	v_mul_f32_e32 v106, v174, v106
	v_add_f32_e32 v174, v15, v183
	v_add_f32_e32 v107, 1.0, v107
	v_max_f32_e32 v175, 0, v175
	v_mul_f32_e32 v174, 0xbfb8aa3b, v174
	v_rcp_f32_e32 v107, v107
	v_sqrt_f32_e32 v175, v175
	v_exp_f32_e32 v174, v174
	v_add_f32_e32 v177, v16, v184
	v_mul_f32_e32 v107, v135, v107
	v_mul_f32_e32 v175, v106, v175
	v_add_f32_e32 v106, 1.0, v174
	v_exp_f32_e32 v174, v107
	v_add_f32_e32 v107, v8, v108
	v_mul_f32_e32 v107, 0xbfb8aa3b, v107
	v_exp_f32_e32 v107, v107
	global_load_dwordx4 v[54:57], v[22:23], off offset:128
	v_fma_f32 v108, -v174, v174, 1.0
	v_rcp_f32_e32 v106, v106
	v_max_f32_e32 v108, 0, v108
	v_add_f32_e32 v107, 1.0, v107
	v_mul_f32_e32 v177, 0xbfb8aa3b, v177
	v_rcp_f32_e32 v107, v107
	v_sqrt_f32_e32 v108, v108
	v_exp_f32_e32 v181, v177
	v_and_b32_e32 v176, 0xffff0000, v198
	v_mul_f32_e32 v106, v106, v176
	v_mul_f32_e32 v107, v132, v107
	v_mul_f32_e32 v177, v106, v108
	v_add_f32_e32 v106, 1.0, v181
	v_exp_f32_e32 v181, v107
	v_add_f32_e32 v107, v9, v109
	global_load_dwordx4 v[46:49], v[22:23], off offset:192
	v_mul_f32_e32 v107, 0xbfb8aa3b, v107
	v_exp_f32_e32 v107, v107
	v_add_f32_e32 v109, v17, v185
	v_mul_f32_e32 v109, 0xbfb8aa3b, v109
	v_exp_f32_e32 v109, v109
	v_add_f32_e32 v107, 1.0, v107
	v_rcp_f32_e32 v107, v107
	v_fma_f32 v108, -v181, v181, 1.0
	v_max_f32_e32 v108, 0, v108
	v_and_b32_e32 v3, 0xffff0000, v199
	v_mul_f32_e32 v107, v133, v107
	v_exp_f32_e32 v176, v107
	v_sqrt_f32_e32 v107, v108
	v_add_f32_e32 v108, 1.0, v109
	v_rcp_f32_e32 v108, v108
	global_load_dwordx4 v[34:37], v[22:23], off offset:256
	v_fma_f32 v109, -v176, v176, 1.0
	v_max_f32_e32 v109, 0, v109
	v_sqrt_f32_e32 v109, v109
	v_mul_f32_e32 v3, v108, v3
	v_add_f32_e32 v108, v18, v192
	v_rcp_f32_e32 v106, v106
	v_mul_f32_e32 v182, v3, v109
	v_add_f32_e32 v3, v10, v188
	v_mul_f32_e32 v3, 0xbfb8aa3b, v3
	v_exp_f32_e32 v3, v3
	v_mul_f32_e32 v108, 0xbfb8aa3b, v108
	v_exp_f32_e32 v108, v108
	v_lshlrev_b32_e32 v186, 16, v199
	v_add_f32_e32 v3, 1.0, v3
	v_rcp_f32_e32 v3, v3
	v_mul_f32_e32 v106, v106, v186
	global_load_dwordx4 v[30:33], v[22:23], off offset:320
	v_mul_f32_e32 v184, v106, v107
	v_lshlrev_b32_e32 v107, 16, v105
	v_mul_f32_e32 v3, v138, v3
	v_exp_f32_e32 v183, v3
	v_and_b32_e32 v3, 0xffff0000, v105
	v_add_f32_e32 v105, 1.0, v108
	v_rcp_f32_e32 v105, v105
	v_lshlrev_b32_e32 v106, 16, v104
	v_fma_f32 v108, -v183, v183, 1.0
	v_add_f32_e32 v109, v19, v193
	v_mul_f32_e32 v105, v105, v106
	v_add_f32_e32 v106, v11, v189
	v_mul_f32_e32 v106, 0xbfb8aa3b, v106
	v_exp_f32_e32 v106, v106
	v_max_f32_e32 v108, 0, v108
	global_load_dwordx4 v[26:29], v[22:23], off offset:384
	v_mul_f32_e32 v109, 0xbfb8aa3b, v109
	v_sqrt_f32_e32 v108, v108
	v_add_f32_e32 v106, 1.0, v106
	v_rcp_f32_e32 v106, v106
	v_exp_f32_e32 v109, v109
	v_mul_f32_e32 v186, v105, v108
	v_and_b32_e32 v104, 0xffff0000, v104
	v_mul_f32_e32 v106, v139, v106
	v_exp_f32_e32 v185, v106
	v_add_f32_e32 v106, v12, v190
	v_mul_f32_e32 v106, 0xbfb8aa3b, v106
	v_exp_f32_e32 v106, v106
	v_add_f32_e32 v105, 1.0, v109
	v_rcp_f32_e32 v105, v105
	v_fma_f32 v108, -v185, v185, 1.0
	s_nop 0
	global_load_dwordx4 v[22:25], v[22:23], off offset:448
	v_add_f32_e32 v106, 1.0, v106
	v_rcp_f32_e32 v106, v106
	v_mul_f32_e32 v104, v105, v104
	v_max_f32_e32 v108, 0, v108
	v_sqrt_f32_e32 v108, v108
	v_mul_f32_e32 v105, v136, v106
	v_exp_f32_e32 v189, v105
	v_add_f32_e32 v105, v13, v191
	v_mul_f32_e32 v105, 0xbfb8aa3b, v105
	v_exp_f32_e32 v105, v105
	v_mul_f32_e32 v188, v104, v108
	v_add_f32_e32 v108, v21, v195
	v_mul_f32_e32 v108, 0xbfb8aa3b, v108
	v_add_f32_e32 v105, 1.0, v105
	v_rcp_f32_e32 v105, v105
	s_nop 0
	v_exp_f32_e32 v108, v108
	v_fma_f32 v106, -v189, v189, 1.0
	v_max_f32_e32 v106, 0, v106
	v_mul_f32_e32 v105, v137, v105
	v_exp_f32_e32 v187, v105
	v_sqrt_f32_e32 v105, v106
	v_add_f32_e32 v106, 1.0, v108
	v_rcp_f32_e32 v106, v106
	v_fma_f32 v108, -v187, v187, 1.0
	v_max_f32_e32 v108, 0, v108
	v_sqrt_f32_e32 v108, v108
	v_mul_f32_e32 v3, v106, v3
	v_add_f32_e32 v109, v20, v194
	v_mul_f32_e32 v109, 0xbfb8aa3b, v109
	v_mul_f32_e32 v190, v3, v108
	v_add_f32_e32 v3, v6, v98
	v_mul_f32_e32 v3, 0xbfb8aa3b, v3
	v_exp_f32_e32 v3, v3
	v_exp_f32_e32 v109, v109
	v_add_f32_e32 v99, v7, v99
	v_mul_f32_e32 v99, 0xbfb8aa3b, v99
	v_add_f32_e32 v3, 1.0, v3
	v_rcp_f32_e32 v3, v3
	v_exp_f32_e32 v99, v99
; __device__ __forceinline__ float bf_lo(unsigned w) { return __uint_as_float(w << 16); }
; __device__ __forceinline__ float bf_hi(unsigned w) { return __uint_as_float(w & 0xffff0000u); }
; __device__ __forceinline__ float sigmoidf_(float x) { return fast_rcp(1.0f + fast_exp(-x)); }
; __device__ __forceinline__ void lru_fused(const bf16* XC, const bf16* Wrg_t, const bf16* PROJ, bf16* YL, const float* b_a, const float* b_x, const float* sp8,
;                                           LAS unsigned char* lds, int tid, int lane, int wave, int vcu, int G) {
;     ...
;             { const size_t rown = (i + 1 < SEQ / 256) ? row0 + 256 : row0;
; #pragma unroll
;                 for (int r2 = 0; r2 < 2; ++r2) { const size_t ro = (rown + 16 * r2 + fr) * D, rg = (rown + 16 * r2 + fr) * NIN;
; #pragma unroll
;                     for (int kb = 0; kb < 8; ++kb) af[r2][kb] = *(const bf16x8*)(abase + ro + 32 * kb);
; #pragma unroll
;                     for (int c2 = 0; c2 < 2; ++c2) { xqn[r2][c2] = *(const v2u*)(xbase + ro + 16 * c2); gqn[r2][c2] = *(const v2u*)(gbase + rg + 16 * c2); } } }
;             float A[2][2][4], U[2][2][4];
; #pragma unroll
;             for (int r2 = 0; r2 < 2; ++r2)
; #pragma unroll
;                 for (int c2 = 0; c2 < 2; ++c2) { const f32x4 rp = acc[r2][c2] + ba[c2], ip = acc[r2][c2 + 2] + bx[c2]; const v2u xw = xq[r2][c2];
;                     const float xv[4] = {bf_lo(xw.x), bf_hi(xw.x), bf_lo(xw.y), bf_hi(xw.y)};
; #pragma unroll
;                     for (int j = 0; j < 4; ++j) { const float r = pg8::sigmoidf_(rp[j]), ig = pg8::sigmoidf_(ip[j]);
;                         const float av = __builtin_amdgcn_exp2f(sp[c2][j] * r);
;                         A[r2][c2][j] = av; U[r2][c2][j] = __builtin_amdgcn_sqrtf(fmaxf(__builtin_fmaf(-av, av, 1.0f), 0.0f)) * (ig * xv[j]); } }
;     ...
; #pragma unroll
;             for (int r2 = 0; r2 < 2; ++r2)
; #pragma unroll
;                 for (int c2 = 0; c2 < 2; ++c2)
;                     asm volatile("s_nop 1\n\t" LRU_STEP(1) LRU_STEP(2) LRU_STEP(4) LRU_STEP(8)
;                                  : "+v"(A[r2][c2][0]), "+v"(A[r2][c2][1]), "+v"(A[r2][c2][2]), "+v"(A[r2][c2][3]), "+v"(U[r2][c2][0]), "+v"(U[r2][c2][1]), "+v"(U[r2][c2][2]), "+v"(U[r2][c2][3]));
	v_add_f32_e32 v104, 1.0, v109
	v_add_f32_e32 v94, v14, v94
	v_rcp_f32_e32 v104, v104
	v_mul_f32_e32 v94, 0xbfb8aa3b, v94
	v_mul_f32_e32 v3, v134, v3
	v_exp_f32_e32 v94, v94
	v_exp_f32_e32 v98, v3
	global_load_dwordx4 v[154:157], v[38:39], off
	v_add_f32_e32 v99, 1.0, v99
	v_add_f32_e32 v101, v9, v101
	v_rcp_f32_e32 v99, v99
	v_mul_f32_e32 v101, 0xbfb8aa3b, v101
	v_exp_f32_e32 v101, v101
	v_mul_f32_e32 v104, v104, v107
	v_mul_f32_e32 v191, v104, v105
	v_lshlrev_b32_e32 v105, 16, v103
	v_and_b32_e32 v3, 0xffff0000, v103
	v_add_f32_e32 v94, 1.0, v94
	v_fma_f32 v103, -v98, v98, 1.0
	v_add_f32_e32 v95, v15, v95
	v_rcp_f32_e32 v94, v94
	v_max_f32_e32 v103, 0, v103
	v_mul_f32_e32 v95, 0xbfb8aa3b, v95
	v_mul_f32_e32 v99, v135, v99
	v_sqrt_f32_e32 v103, v103
	v_exp_f32_e32 v95, v95
	v_exp_f32_e32 v99, v99
	v_add_f32_e32 v100, v8, v100
	v_add_f32_e32 v101, 1.0, v101
	v_mul_f32_e32 v100, 0xbfb8aa3b, v100
	v_rcp_f32_e32 v101, v101
	v_lshlrev_b32_e32 v104, 16, v102
	v_exp_f32_e32 v100, v100
	v_mul_f32_e32 v94, v94, v104
	v_mul_f32_e32 v94, v94, v103
	v_add_f32_e32 v95, 1.0, v95
	v_fma_f32 v103, -v99, v99, 1.0
	v_add_f32_e32 v97, v17, v97
	v_rcp_f32_e32 v95, v95
	v_lshl_add_u64 v[38:39], v[110:111], 0, s[24:25]
	v_lshl_add_u64 v[148:149], v[38:39], 0, 16
	v_lshlrev_b64 v[150:151], 13, v[148:149]
	v_lshl_add_u64 v[38:39], v[122:123], 0, v[150:151]
	v_mad_u64_u32 v[162:163], s[24:25], v148, s13, v[126:127]
	v_mov_b32_e32 v148, v163
	v_mad_u64_u32 v[148:149], s[24:25], v149, s13, v[148:149]
	v_lshl_add_u64 v[150:151], v[124:125], 0, v[150:151]
	v_mov_b32_e32 v163, v148
	v_max_f32_e32 v103, 0, v103
	v_mul_f32_e32 v97, 0xbfb8aa3b, v97
	v_mul_f32_e32 v101, v133, v101
	v_sqrt_f32_e32 v103, v103
	v_add_f32_e32 v100, 1.0, v100
	v_exp_f32_e32 v97, v97
	v_exp_f32_e32 v101, v101
	v_rcp_f32_e32 v100, v100
	v_and_b32_e32 v102, 0xffff0000, v102
	v_mul_f32_e32 v95, v95, v102
	v_add_f32_e32 v96, v16, v96
	v_mul_f32_e32 v95, v95, v103
	v_add_f32_e32 v97, 1.0, v97
	v_fma_f32 v103, -v101, v101, 1.0
	v_mul_f32_e32 v96, 0xbfb8aa3b, v96
	s_nop 0
	global_load_dwordx4 v[160:163], v[162:163], off
	v_mul_f32_e32 v100, v132, v100
	v_rcp_f32_e32 v97, v97
	v_max_f32_e32 v103, 0, v103
	v_exp_f32_e32 v96, v96
	v_exp_f32_e32 v100, v100
	v_sqrt_f32_e32 v103, v103
	v_mul_f32_e32 v3, v97, v3
	v_add_f32_e32 v96, 1.0, v96
	v_fma_f32 v102, -v100, v100, 1.0
	v_mul_f32_e32 v97, v3, v103
	v_add_f32_e32 v3, v10, v90
	v_rcp_f32_e32 v96, v96
	v_max_f32_e32 v102, 0, v102
	v_mul_f32_e32 v3, 0xbfb8aa3b, v3
	v_sqrt_f32_e32 v102, v102
	v_exp_f32_e32 v3, v3
	v_mul_f32_e32 v96, v96, v105
	v_lshlrev_b32_e32 v90, 16, v4
	v_mul_f32_e32 v96, v96, v102
	v_and_b32_e32 v102, 0xffff0000, v4
	v_add_f32_e32 v3, 1.0, v3
	v_add_f32_e32 v4, v18, v86
	v_rcp_f32_e32 v3, v3
	v_mul_f32_e32 v4, 0xbfb8aa3b, v4
	v_exp_f32_e32 v86, v4
	v_lshlrev_b32_e32 v103, 16, v5
	v_mul_f32_e32 v3, v138, v3
	v_exp_f32_e32 v4, v3
	v_and_b32_e32 v3, 0xffff0000, v5
	v_add_f32_e32 v5, 1.0, v86
	v_rcp_f32_e32 v5, v5
	v_fma_f32 v86, -v4, v4, 1.0
	v_add_f32_e32 v87, v19, v87
	v_max_f32_e32 v86, 0, v86
	v_mul_f32_e32 v5, v5, v90
	v_add_f32_e32 v90, v11, v91
	v_mul_f32_e32 v90, 0xbfb8aa3b, v90
	v_exp_f32_e32 v90, v90
	v_mul_f32_e32 v87, 0xbfb8aa3b, v87
	v_sqrt_f32_e32 v86, v86
	v_exp_f32_e32 v87, v87
	v_add_f32_e32 v90, 1.0, v90
	v_rcp_f32_e32 v90, v90
	v_mul_f32_e32 v86, v5, v86
	v_add_f32_e32 v5, 1.0, v87
	v_rcp_f32_e32 v87, v5
	global_load_dwordx4 v[82:85], v[38:39], off
	v_mul_f32_e32 v5, v139, v90
	v_add_f32_e32 v90, v12, v92
	v_mul_f32_e32 v90, 0xbfb8aa3b, v90
	v_exp_f32_e32 v90, v90
	v_exp_f32_e32 v5, v5
	v_add_f32_e32 v88, v20, v88
	v_add_f32_e32 v89, v21, v89
	v_add_f32_e32 v90, 1.0, v90
	v_rcp_f32_e32 v90, v90
	v_fma_f32 v91, -v5, v5, 1.0
	v_max_f32_e32 v91, 0, v91
	v_sqrt_f32_e32 v91, v91
	v_mul_f32_e32 v90, v136, v90
	v_exp_f32_e32 v92, v90
	v_add_f32_e32 v90, v13, v93
	global_load_dwordx4 v[78:81], v[38:39], off offset:64
	v_mul_f32_e32 v90, 0xbfb8aa3b, v90
	v_exp_f32_e32 v90, v90
	v_mul_f32_e32 v88, 0xbfb8aa3b, v88
	v_mul_f32_e32 v89, 0xbfb8aa3b, v89
	v_exp_f32_e32 v88, v88
	v_add_f32_e32 v90, 1.0, v90
	v_rcp_f32_e32 v90, v90
	v_exp_f32_e32 v89, v89
	v_mul_f32_e32 v87, v87, v102
	v_mul_f32_e32 v87, v87, v91
	v_mul_f32_e32 v90, v137, v90
	v_exp_f32_e32 v93, v90
	v_fma_f32 v91, -v92, v92, 1.0
	v_max_f32_e32 v91, 0, v91
	v_add_f32_e32 v88, 1.0, v88
	global_load_dwordx4 v[74:77], v[38:39], off offset:128
	v_sqrt_f32_e32 v90, v91
	v_add_f32_e32 v89, 1.0, v89
	v_fma_f32 v91, -v93, v93, 1.0
	v_rcp_f32_e32 v88, v88
	v_rcp_f32_e32 v89, v89
	v_max_f32_e32 v91, 0, v91
	v_sqrt_f32_e32 v91, v91
	v_mul_f32_e32 v88, v88, v103
	v_mul_f32_e32 v3, v89, v3
	v_mul_f32_e32 v88, v88, v90
	v_mul_f32_e32 v89, v3, v91
	s_nop 1
	v_fmac_f32_dpp v175, v175, v173 row_shr:1 row_mask:0xf bank_mask:0xf
	v_mul_f32_dpp v173, v173, v173 row_shr:1 row_mask:0xf bank_mask:0xf
	v_fmac_f32_dpp v177, v177, v174 row_shr:1 row_mask:0xf bank_mask:0xf
	v_mul_f32_dpp v174, v174, v174 row_shr:1 row_mask:0xf bank_mask:0xf
	global_load_dwordx4 v[66:69], v[38:39], off offset:192
	v_fmac_f32_dpp v184, v184, v181 row_shr:1 row_mask:0xf bank_mask:0xf
	v_mul_f32_dpp v181, v181, v181 row_shr:1 row_mask:0xf bank_mask:0xf
	v_fmac_f32_dpp v182, v182, v176 row_shr:1 row_mask:0xf bank_mask:0xf
	v_mul_f32_dpp v176, v176, v176 row_shr:1 row_mask:0xf bank_mask:0xf
	v_fmac_f32_dpp v175, v175, v173 row_shr:2 row_mask:0xf bank_mask:0xf
	v_mul_f32_dpp v173, v173, v173 row_shr:2 row_mask:0xf bank_mask:0xf
	v_fmac_f32_dpp v177, v177, v174 row_shr:2 row_mask:0xf bank_mask:0xf
	v_mul_f32_dpp v174, v174, v174 row_shr:2 row_mask:0xf bank_mask:0xf
	v_fmac_f32_dpp v184, v184, v181 row_shr:2 row_mask:0xf bank_mask:0xf
	v_mul_f32_dpp v181, v181, v181 row_shr:2 row_mask:0xf bank_mask:0xf
	v_fmac_f32_dpp v182, v182, v176 row_shr:2 row_mask:0xf bank_mask:0xf
	v_mul_f32_dpp v176, v176, v176 row_shr:2 row_mask:0xf bank_mask:0xf
	v_fmac_f32_dpp v175, v175, v173 row_shr:4 row_mask:0xf bank_mask:0xf
	v_mul_f32_dpp v173, v173, v173 row_shr:4 row_mask:0xf bank_mask:0xf
	v_fmac_f32_dpp v177, v177, v174 row_shr:4 row_mask:0xf bank_mask:0xf
	global_load_dwordx4 v[58:61], v[38:39], off offset:256
	v_mul_f32_dpp v174, v174, v174 row_shr:4 row_mask:0xf bank_mask:0xf
	v_fmac_f32_dpp v184, v184, v181 row_shr:4 row_mask:0xf bank_mask:0xf
	v_mul_f32_dpp v181, v181, v181 row_shr:4 row_mask:0xf bank_mask:0xf
	v_fmac_f32_dpp v182, v182, v176 row_shr:4 row_mask:0xf bank_mask:0xf
	v_mul_f32_dpp v176, v176, v176 row_shr:4 row_mask:0xf bank_mask:0xf
	v_fmac_f32_dpp v175, v175, v173 row_shr:8 row_mask:0xf bank_mask:0xf
	v_mul_f32_dpp v173, v173, v173 row_shr:8 row_mask:0xf bank_mask:0xf
	v_fmac_f32_dpp v177, v177, v174 row_shr:8 row_mask:0xf bank_mask:0xf
	v_mul_f32_dpp v174, v174, v174 row_shr:8 row_mask:0xf bank_mask:0xf
	v_fmac_f32_dpp v184, v184, v181 row_shr:8 row_mask:0xf bank_mask:0xf
	v_mul_f32_dpp v181, v181, v181 row_shr:8 row_mask:0xf bank_mask:0xf
	v_fmac_f32_dpp v182, v182, v176 row_shr:8 row_mask:0xf bank_mask:0xf
	v_mul_f32_dpp v176, v176, v176 row_shr:8 row_mask:0xf bank_mask:0xf

; __device__ __forceinline__ float bf_lo(unsigned w) { return __uint_as_float(w << 16); }
; __device__ __forceinline__ float bf_hi(unsigned w) { return __uint_as_float(w & 0xffff0000u); }
; __device__ __forceinline__ float sigmoidf_(float x) { return fast_rcp(1.0f + fast_exp(-x)); }
; __device__ __forceinline__ void lru_fused(const bf16* XC, const bf16* Wrg_t, const bf16* PROJ, bf16* YL, const float* b_a, const float* b_x, const float* sp8,
;                                           LAS unsigned char* lds, int tid, int lane, int wave, int vcu, int G) {
;     ...
;                 for (int r2 = 0; r2 < 2; ++r2) { const size_t ro = (rown + 16 * r2 + fr) * D, rg = (rown + 16 * r2 + fr) * NIN;
; #pragma unroll
;                     for (int kb = 0; kb < 8; ++kb) af[r2][kb] = *(const bf16x8*)(abase + ro + 32 * kb);
; #pragma unroll
;                     for (int c2 = 0; c2 < 2; ++c2) { xqn[r2][c2] = *(const v2u*)(xbase + ro + 16 * c2); gqn[r2][c2] = *(const v2u*)(gbase + rg + 16 * c2); } } }
;             float A[2][2][4], U[2][2][4];
; #pragma unroll
;             for (int r2 = 0; r2 < 2; ++r2)
; #pragma unroll
;                 for (int c2 = 0; c2 < 2; ++c2) { const f32x4 rp = acc[r2][c2] + ba[c2], ip = acc[r2][c2 + 2] + bx[c2]; const v2u xw = xq[r2][c2];
;                     const float xv[4] = {bf_lo(xw.x), bf_hi(xw.x), bf_lo(xw.y), bf_hi(xw.y)};
; #pragma unroll
;                     for (int j = 0; j < 4; ++j) { const float r = pg8::sigmoidf_(rp[j]), ig = pg8::sigmoidf_(ip[j]);
;                         const float av = __builtin_amdgcn_exp2f(sp[c2][j] * r);
;                         A[r2][c2][j] = av; U[r2][c2][j] = __builtin_amdgcn_sqrtf(fmaxf(__builtin_fmaf(-av, av, 1.0f), 0.0f)) * (ig * xv[j]); } }
;     ...
; #pragma unroll
;             for (int r2 = 0; r2 < 2; ++r2)
; #pragma unroll
;                 for (int c2 = 0; c2 < 2; ++c2)
;                     asm volatile("s_nop 1\n\t" LRU_STEP(1) LRU_STEP(2) LRU_STEP(4) LRU_STEP(8)
;                                  : "+v"(A[r2][c2][0]), "+v"(A[r2][c2][1]), "+v"(A[r2][c2][2]), "+v"(A[r2][c2][3]), "+v"(U[r2][c2][0]), "+v"(U[r2][c2][1]), "+v"(U[r2][c2][2]), "+v"(U[r2][c2][3]));
;     ...
;             const int l15 = (lane & 48) | 15;
; #pragma unroll
;             for (int c2 = 0; c2 < 2; ++c2)
; #pragma unroll
;                 for (int j = 0; j < 4; ++j) { const float a15 = __shfl(A[0][c2][j], l15), u15 = __shfl(U[0][c2][j], l15);
	ds_bpermute_b32 v90, v172, v173
	ds_bpermute_b32 v102, v172, v175
	global_load_dwordx4 v[50:53], v[38:39], off offset:320
	ds_bpermute_b32 v103, v172, v177
	ds_bpermute_b32 v91, v172, v174
	ds_bpermute_b32 v104, v172, v184
	ds_bpermute_b32 v105, v172, v182
	s_nop 1
	v_fmac_f32_dpp v186, v186, v183 row_shr:1 row_mask:0xf bank_mask:0xf
	v_mul_f32_dpp v183, v183, v183 row_shr:1 row_mask:0xf bank_mask:0xf
	v_fmac_f32_dpp v188, v188, v185 row_shr:1 row_mask:0xf bank_mask:0xf
	v_mul_f32_dpp v185, v185, v185 row_shr:1 row_mask:0xf bank_mask:0xf
	v_fmac_f32_dpp v191, v191, v189 row_shr:1 row_mask:0xf bank_mask:0xf
	v_mul_f32_dpp v189, v189, v189 row_shr:1 row_mask:0xf bank_mask:0xf
	v_fmac_f32_dpp v190, v190, v187 row_shr:1 row_mask:0xf bank_mask:0xf
	v_mul_f32_dpp v187, v187, v187 row_shr:1 row_mask:0xf bank_mask:0xf
	v_fmac_f32_dpp v186, v186, v183 row_shr:2 row_mask:0xf bank_mask:0xf
	v_mul_f32_dpp v183, v183, v183 row_shr:2 row_mask:0xf bank_mask:0xf
	v_fmac_f32_dpp v188, v188, v185 row_shr:2 row_mask:0xf bank_mask:0xf
	global_load_dwordx4 v[42:45], v[38:39], off offset:384
	v_mul_f32_dpp v185, v185, v185 row_shr:2 row_mask:0xf bank_mask:0xf
	v_fmac_f32_dpp v191, v191, v189 row_shr:2 row_mask:0xf bank_mask:0xf
	v_mul_f32_dpp v189, v189, v189 row_shr:2 row_mask:0xf bank_mask:0xf
	v_fmac_f32_dpp v190, v190, v187 row_shr:2 row_mask:0xf bank_mask:0xf
	v_mul_f32_dpp v187, v187, v187 row_shr:2 row_mask:0xf bank_mask:0xf
	v_fmac_f32_dpp v186, v186, v183 row_shr:4 row_mask:0xf bank_mask:0xf
	v_mul_f32_dpp v183, v183, v183 row_shr:4 row_mask:0xf bank_mask:0xf
	v_fmac_f32_dpp v188, v188, v185 row_shr:4 row_mask:0xf bank_mask:0xf
	v_mul_f32_dpp v185, v185, v185 row_shr:4 row_mask:0xf bank_mask:0xf
	v_fmac_f32_dpp v191, v191, v189 row_shr:4 row_mask:0xf bank_mask:0xf
	v_mul_f32_dpp v189, v189, v189 row_shr:4 row_mask:0xf bank_mask:0xf
	v_fmac_f32_dpp v190, v190, v187 row_shr:4 row_mask:0xf bank_mask:0xf
	v_mul_f32_dpp v187, v187, v187 row_shr:4 row_mask:0xf bank_mask:0xf
	v_fmac_f32_dpp v186, v186, v183 row_shr:8 row_mask:0xf bank_mask:0xf
	v_mul_f32_dpp v183, v183, v183 row_shr:8 row_mask:0xf bank_mask:0xf
	s_nop 0
	global_load_dwordx4 v[38:41], v[38:39], off offset:448
	v_fmac_f32_dpp v188, v188, v185 row_shr:8 row_mask:0xf bank_mask:0xf
	v_mul_f32_dpp v185, v185, v185 row_shr:8 row_mask:0xf bank_mask:0xf
	v_fmac_f32_dpp v191, v191, v189 row_shr:8 row_mask:0xf bank_mask:0xf
	v_mul_f32_dpp v189, v189, v189 row_shr:8 row_mask:0xf bank_mask:0xf
	v_fmac_f32_dpp v190, v190, v187 row_shr:8 row_mask:0xf bank_mask:0xf
	v_mul_f32_dpp v187, v187, v187 row_shr:8 row_mask:0xf bank_mask:0xf

; __device__ __forceinline__ void lru_fused(const bf16* XC, const bf16* Wrg_t, const bf16* PROJ, bf16* YL, const float* b_a, const float* b_x, const float* sp8,
;                                           LAS unsigned char* lds, int tid, int lane, int wave, int vcu, int G) {
;     ...
;             for (int r2 = 0; r2 < 2; ++r2)
; #pragma unroll
;                 for (int c2 = 0; c2 < 2; ++c2)
;                     asm volatile("s_nop 1\n\t" LRU_STEP(1) LRU_STEP(2) LRU_STEP(4) LRU_STEP(8)
;                                  : "+v"(A[r2][c2][0]), "+v"(A[r2][c2][1]), "+v"(A[r2][c2][2]), "+v"(A[r2][c2][3]), "+v"(U[r2][c2][0]), "+v"(U[r2][c2][1]), "+v"(U[r2][c2][2]), "+v"(U[r2][c2][3]));
	s_nop 1
	v_fmac_f32_dpp v94, v94, v98 row_shr:1 row_mask:0xf bank_mask:0xf
	v_mul_f32_dpp v98, v98, v98 row_shr:1 row_mask:0xf bank_mask:0xf
	v_fmac_f32_dpp v95, v95, v99 row_shr:1 row_mask:0xf bank_mask:0xf
	v_mul_f32_dpp v99, v99, v99 row_shr:1 row_mask:0xf bank_mask:0xf
	v_fmac_f32_dpp v96, v96, v100 row_shr:1 row_mask:0xf bank_mask:0xf
	v_mul_f32_dpp v100, v100, v100 row_shr:1 row_mask:0xf bank_mask:0xf
	v_fmac_f32_dpp v97, v97, v101 row_shr:1 row_mask:0xf bank_mask:0xf
	v_mul_f32_dpp v101, v101, v101 row_shr:1 row_mask:0xf bank_mask:0xf
	v_fmac_f32_dpp v94, v94, v98 row_shr:2 row_mask:0xf bank_mask:0xf
	v_mul_f32_dpp v98, v98, v98 row_shr:2 row_mask:0xf bank_mask:0xf
	v_fmac_f32_dpp v95, v95, v99 row_shr:2 row_mask:0xf bank_mask:0xf
	v_mul_f32_dpp v99, v99, v99 row_shr:2 row_mask:0xf bank_mask:0xf
	v_fmac_f32_dpp v96, v96, v100 row_shr:2 row_mask:0xf bank_mask:0xf
	v_mul_f32_dpp v100, v100, v100 row_shr:2 row_mask:0xf bank_mask:0xf
	v_fmac_f32_dpp v97, v97, v101 row_shr:2 row_mask:0xf bank_mask:0xf
	v_mul_f32_dpp v101, v101, v101 row_shr:2 row_mask:0xf bank_mask:0xf
	v_fmac_f32_dpp v94, v94, v98 row_shr:4 row_mask:0xf bank_mask:0xf
	v_mul_f32_dpp v98, v98, v98 row_shr:4 row_mask:0xf bank_mask:0xf
	v_fmac_f32_dpp v95, v95, v99 row_shr:4 row_mask:0xf bank_mask:0xf
	v_mul_f32_dpp v99, v99, v99 row_shr:4 row_mask:0xf bank_mask:0xf
	v_fmac_f32_dpp v96, v96, v100 row_shr:4 row_mask:0xf bank_mask:0xf
	v_mul_f32_dpp v100, v100, v100 row_shr:4 row_mask:0xf bank_mask:0xf
	v_fmac_f32_dpp v97, v97, v101 row_shr:4 row_mask:0xf bank_mask:0xf
	v_mul_f32_dpp v101, v101, v101 row_shr:4 row_mask:0xf bank_mask:0xf
	v_fmac_f32_dpp v94, v94, v98 row_shr:8 row_mask:0xf bank_mask:0xf
	v_mul_f32_dpp v98, v98, v98 row_shr:8 row_mask:0xf bank_mask:0xf
	v_fmac_f32_dpp v95, v95, v99 row_shr:8 row_mask:0xf bank_mask:0xf
	v_mul_f32_dpp v99, v99, v99 row_shr:8 row_mask:0xf bank_mask:0xf
	v_fmac_f32_dpp v96, v96, v100 row_shr:8 row_mask:0xf bank_mask:0xf
	v_mul_f32_dpp v100, v100, v100 row_shr:8 row_mask:0xf bank_mask:0xf
	v_fmac_f32_dpp v97, v97, v101 row_shr:8 row_mask:0xf bank_mask:0xf
	v_mul_f32_dpp v101, v101, v101 row_shr:8 row_mask:0xf bank_mask:0xf

; __device__ __forceinline__ void lru_fused(const bf16* XC, const bf16* Wrg_t, const bf16* PROJ, bf16* YL, const float* b_a, const float* b_x, const float* sp8,
;                                           LAS unsigned char* lds, int tid, int lane, int wave, int vcu, int G) {
;     ...
;             for (int r2 = 0; r2 < 2; ++r2)
; #pragma unroll
;                 for (int c2 = 0; c2 < 2; ++c2)
;                     asm volatile("s_nop 1\n\t" LRU_STEP(1) LRU_STEP(2) LRU_STEP(4) LRU_STEP(8)
;                                  : "+v"(A[r2][c2][0]), "+v"(A[r2][c2][1]), "+v"(A[r2][c2][2]), "+v"(A[r2][c2][3]), "+v"(U[r2][c2][0]), "+v"(U[r2][c2][1]), "+v"(U[r2][c2][2]), "+v"(U[r2][c2][3]));
;     ...
;             const int l15 = (lane & 48) | 15;
; #pragma unroll
;             for (int c2 = 0; c2 < 2; ++c2)
; #pragma unroll
;                 for (int j = 0; j < 4; ++j) { const float a15 = __shfl(A[0][c2][j], l15), u15 = __shfl(U[0][c2][j], l15);
;                     U[1][c2][j] = A[1][c2][j] * u15 + U[1][c2][j]; A[1][c2][j] = A[1][c2][j] * a15; }
	ds_bpermute_b32 v106, v172, v189
	s_waitcnt lgkmcnt(4)
	v_pk_fma_f32 v[94:95], v[98:99], v[102:103], v[94:95]
	s_waitcnt lgkmcnt(3)
	v_pk_mul_f32 v[98:99], v[98:99], v[90:91]
	ds_bpermute_b32 v90, v172, v181
	ds_bpermute_b32 v91, v172, v176
	s_waitcnt lgkmcnt(3)
	v_pk_fma_f32 v[96:97], v[100:101], v[104:105], v[96:97]
	ds_bpermute_b32 v102, v172, v183
	ds_bpermute_b32 v104, v172, v186
	ds_bpermute_b32 v103, v172, v185
	ds_bpermute_b32 v105, v172, v188
	ds_bpermute_b32 v108, v172, v191
	ds_bpermute_b32 v109, v172, v190
	ds_bpermute_b32 v107, v172, v187
	s_and_b32 s24, s22, 1
	s_nop 1
	v_fmac_f32_dpp v86, v86, v4 row_shr:1 row_mask:0xf bank_mask:0xf
	v_mul_f32_dpp v4, v4, v4 row_shr:1 row_mask:0xf bank_mask:0xf
	v_fmac_f32_dpp v87, v87, v5 row_shr:1 row_mask:0xf bank_mask:0xf
	v_mul_f32_dpp v5, v5, v5 row_shr:1 row_mask:0xf bank_mask:0xf
	v_fmac_f32_dpp v88, v88, v92 row_shr:1 row_mask:0xf bank_mask:0xf
	v_mul_f32_dpp v92, v92, v92 row_shr:1 row_mask:0xf bank_mask:0xf
	v_fmac_f32_dpp v89, v89, v93 row_shr:1 row_mask:0xf bank_mask:0xf
	v_mul_f32_dpp v93, v93, v93 row_shr:1 row_mask:0xf bank_mask:0xf
	v_fmac_f32_dpp v86, v86, v4 row_shr:2 row_mask:0xf bank_mask:0xf
	v_mul_f32_dpp v4, v4, v4 row_shr:2 row_mask:0xf bank_mask:0xf
	v_fmac_f32_dpp v87, v87, v5 row_shr:2 row_mask:0xf bank_mask:0xf
	v_mul_f32_dpp v5, v5, v5 row_shr:2 row_mask:0xf bank_mask:0xf
	v_fmac_f32_dpp v88, v88, v92 row_shr:2 row_mask:0xf bank_mask:0xf
	v_mul_f32_dpp v92, v92, v92 row_shr:2 row_mask:0xf bank_mask:0xf
	v_fmac_f32_dpp v89, v89, v93 row_shr:2 row_mask:0xf bank_mask:0xf
	v_mul_f32_dpp v93, v93, v93 row_shr:2 row_mask:0xf bank_mask:0xf
	v_fmac_f32_dpp v86, v86, v4 row_shr:4 row_mask:0xf bank_mask:0xf
	v_mul_f32_dpp v4, v4, v4 row_shr:4 row_mask:0xf bank_mask:0xf
	v_fmac_f32_dpp v87, v87, v5 row_shr:4 row_mask:0xf bank_mask:0xf
	v_mul_f32_dpp v5, v5, v5 row_shr:4 row_mask:0xf bank_mask:0xf
	v_fmac_f32_dpp v88, v88, v92 row_shr:4 row_mask:0xf bank_mask:0xf
	v_mul_f32_dpp v92, v92, v92 row_shr:4 row_mask:0xf bank_mask:0xf
	v_fmac_f32_dpp v89, v89, v93 row_shr:4 row_mask:0xf bank_mask:0xf
	v_mul_f32_dpp v93, v93, v93 row_shr:4 row_mask:0xf bank_mask:0xf
	v_fmac_f32_dpp v86, v86, v4 row_shr:8 row_mask:0xf bank_mask:0xf
	v_mul_f32_dpp v4, v4, v4 row_shr:8 row_mask:0xf bank_mask:0xf
	v_fmac_f32_dpp v87, v87, v5 row_shr:8 row_mask:0xf bank_mask:0xf
	v_mul_f32_dpp v5, v5, v5 row_shr:8 row_mask:0xf bank_mask:0xf
	v_fmac_f32_dpp v88, v88, v92 row_shr:8 row_mask:0xf bank_mask:0xf
	v_mul_f32_dpp v92, v92, v92 row_shr:8 row_mask:0xf bank_mask:0xf
	v_fmac_f32_dpp v89, v89, v93 row_shr:8 row_mask:0xf bank_mask:0xf
	v_mul_f32_dpp v93, v93, v93 row_shr:8 row_mask:0xf bank_mask:0xf

; #define LAS __attribute__((address_space(3)))
; __device__ __forceinline__ void lru_fused(const bf16* XC, const bf16* Wrg_t, const bf16* PROJ, bf16* YL, const float* b_a, const float* b_x, const float* sp8,
;                                           LAS unsigned char* lds, int tid, int lane, int wave, int vcu, int G) {
;     ...
;             const int l15 = (lane & 48) | 15;
; #pragma unroll
;             for (int c2 = 0; c2 < 2; ++c2)
; #pragma unroll
;                 for (int j = 0; j < 4; ++j) { const float a15 = __shfl(A[0][c2][j], l15), u15 = __shfl(U[0][c2][j], l15);
;                     U[1][c2][j] = A[1][c2][j] * u15 + U[1][c2][j]; A[1][c2][j] = A[1][c2][j] * a15; }
;             LAS float* xp = xch + (i & 1) * 512;
;             if (fr == 15) {
; #pragma unroll
;                 for (int c2 = 0; c2 < 2; ++c2) { *(LAS f32x4*)(xp + wave * 32 + 16 * c2 + 4 * fq) = (f32x4){A[1][c2][0], A[1][c2][1], A[1][c2][2], A[1][c2][3]};
;                     *(LAS f32x4*)(xp + 256 + wave * 32 + 16 * c2 + 4 * fq) = (f32x4){U[1][c2][0], U[1][c2][1], U[1][c2][2], U[1][c2][3]}; } }
	s_lshl_b32 s23, s24, 11
	s_waitcnt lgkmcnt(7)
	v_pk_mul_f32 v[100:101], v[100:101], v[90:91]
	s_waitcnt lgkmcnt(3)
	v_pk_fma_f32 v[86:87], v[4:5], v[104:105], v[86:87]
	v_pk_mul_f32 v[90:91], v[4:5], v[102:103]
	s_waitcnt lgkmcnt(1)
	v_pk_fma_f32 v[88:89], v[92:93], v[108:109], v[88:89]
	s_waitcnt lgkmcnt(0)
	v_pk_mul_f32 v[92:93], v[92:93], v[106:107]
	s_add_i32 s23, s23, 0
	s_and_saveexec_b64 s[66:67], s[2:3]
	s_cbranch_execz .LBB0_458
	s_lshl_b32 s25, s6, 2
	s_add_i32 s25, s23, s25
	v_lshl_add_u32 v3, v165, 2, s25
	ds_write_b128 v3, v[98:101] offset:36864
	ds_write_b128 v3, v[94:97] offset:37888
	ds_write_b128 v3, v[90:93] offset:36928
	ds_write_b128 v3, v[86:89] offset:37952
